# phase-0 weight-tile prep loop rewritten by hand: scalar tile math, saddr loads, all 4 chunk + 4 scale loads in flight, next-tile prefetch
# baseline (speedup 1.0000x reference)
.LBB0_433:
	s_and_b64 vcc, exec, s[8:9]
	s_cbranch_vccz .LBB0_496
	s_waitcnt lgkmcnt(0)
	s_mov_b64 s[8:9], exec
	v_lshrrev_b32_e32 v0, 8, v141
	v_readlane_b32 s0, v255, 9
	v_readfirstlane_b32 s12, v0
	v_and_b32_e32 v8, 15, v141
	v_lshlrev_b32_e32 v8, 4, v8
	v_bfe_u32 v29, v141, 4, 4
	v_and_b32_e32 v20, 7, v141
	v_mul_u32_u24_e32 v1, 0x820, v20
	v_lshlrev_b32_e32 v20, 4, v20
	v_bfe_u32 v33, v141, 3, 5
	s_add_i32 s13, s0, s12
	s_lshl_b32 s0, s12, 16
	s_add_i32 s0, s0, 16
	v_mul_u32_u24_e32 v32, 0x104, v29
	v_add3_u32 v30, v8, v32, s0
	v_add_u32_e32 v47, 0x1040, v30
	v_add_u32_e32 v48, 0x2080, v30
	v_add_u32_e32 v49, 0x30c0, v30
	v_lshl_add_u32 v34, v33, 2, v1
	v_add_u32_e32 v34, s0, v34
	v_add_u32_e32 v35, 0x400, v34
	v_lshl_add_u32 v40, v29, 12, v8
	v_lshl_add_u32 v41, v29, 13, v8
	v_mad_u32_u24 v42, v29, s63, v8
	v_lshl_add_u32 v43, v33, 11, v20
	v_mov_b32_e32 v0, 0x1600
	v_mad_u32_u24 v44, v33, v0, v20
	v_lshlrev_b32_e32 v45, 2, v29
	s_mov_b32 s12, 0
	s_mov_b32 s14, 0
.Lp0_loop:
	s_cmp_eq_u32 s12, 0
	s_cbranch_scc1 .Lp0_pf
	s_cmp_eq_u32 s12, 1
	s_cbranch_scc0 .Lp0_w2
	s_waitcnt vmcnt(0)
.Lp0_w2:
	s_waitcnt vmcnt(2)
	s_cmp_eq_u32 s14, 0
	s_cbranch_scc1 .Lp0_wr
	v_pk_mul_f32 v[52:53], v[52:53], v[68:69] op_sel_hi:[1,0]
	v_pk_mul_f32 v[54:55], v[54:55], v[68:69] op_sel_hi:[1,0]
	v_pk_mul_f32 v[56:57], v[56:57], v[70:71] op_sel_hi:[1,0]
	v_pk_mul_f32 v[58:59], v[58:59], v[70:71] op_sel_hi:[1,0]
	v_pk_mul_f32 v[60:61], v[60:61], v[72:73] op_sel_hi:[1,0]
	v_pk_mul_f32 v[62:63], v[62:63], v[72:73] op_sel_hi:[1,0]
	v_pk_mul_f32 v[64:65], v[64:65], v[74:75] op_sel_hi:[1,0]
	v_pk_mul_f32 v[66:67], v[66:67], v[74:75] op_sel_hi:[1,0]
.Lp0_wr:
	ds_write2_b32 v30, v52, v53 offset1:1
	ds_write2_b32 v30, v54, v55 offset0:2 offset1:3
	ds_write2_b32 v47, v56, v57 offset1:1
	ds_write2_b32 v47, v58, v59 offset0:2 offset1:3
	ds_write2_b32 v48, v60, v61 offset1:1
	ds_write2_b32 v48, v62, v63 offset0:2 offset1:3
	ds_write2_b32 v49, v64, v65 offset1:1
	ds_write2_b32 v49, v66, v67 offset0:2 offset1:3
.Lp0_pf:
	s_cmpk_ge_u32 s13, 0xc40
	s_cbranch_scc1 .Lp0_s2
	s_cmpk_ge_u32 s13, 0x840
	s_cbranch_scc1 .Lp0_tA
	s_cmpk_ge_u32 s13, 0x580
	s_cbranch_scc1 .Lp0_twd
	s_sub_u32 s0, s13, 0x2c0
	v_readlane_b32 s40, v252, 16
	v_readlane_b32 s41, v252, 17
	v_readlane_b32 s42, v252, 18
	v_readlane_b32 s43, v252, 19
	s_cmp_lt_u32 s0, s62
	s_cselect_b32 s18, 1, 0
	s_cselect_b32 s1, s0, s13
	s_cselect_b64 s[40:41], s[42:43], s[40:41]
	s_and_b32 s0, s1, 15
	s_lshr_b32 s1, s1, 4
	s_lshl_b32 s19, s1, 8
	s_mul_i32 s15, s0, s63
	s_lshl_b32 s15, s15, 6
	s_add_u32 s15, s15, s19
	s_add_u32 s40, s40, s15
	s_addc_u32 s41, s41, 0
	s_lshl_b32 s42, s63, 4
	v_readlane_b32 s48, v252, 14
	v_readlane_b32 s49, v252, 15
	s_lshl_b32 s15, s0, 8
	s_add_u32 s48, s48, s15
	s_addc_u32 s49, s49, 0
	s_mov_b32 s50, 1
	s_and_b64 s[52:53], s[60:61], exec
	s_cselect_b32 s51, 1, 0
	s_lshr_b32 s15, s1, 1
	s_lshl_b32 s15, s15, 8
	s_and_b32 s19, s1, 1
	s_lshl_b32 s19, s19, 6
	s_add_u32 s15, s15, s19
	s_lshl_b32 s19, s18, 7
	s_add_u32 s15, s15, s19
	s_lshl_b32 s15, s15, 11
	s_lshl_b32 s19, s0, 7
	s_add_u32 s15, s15, s19
	s_add_u32 s44, s88, s15
	s_addc_u32 s45, s89, 0
	s_add_u32 s46, s44, 0x10000
	s_addc_u32 s47, s45, 0
	v_mov_b32_e32 v50, v42
	v_mov_b32_e32 v51, v43
	s_branch .Lp0_issue
.Lp0_twd:
	s_sub_u32 s0, s13, 0x580
	s_mul_hi_u32 s1, s0, 0xba2e8ba3
	s_lshr_b32 s1, s1, 5
	s_mul_i32 s15, s1, 44
	s_sub_u32 s0, s0, s15
	v_readlane_b32 s40, v252, 20
	v_readlane_b32 s41, v252, 21
	s_lshl_b32 s15, s1, 8
	s_lshl_b32 s19, s0, 18
	s_add_u32 s15, s15, s19
	s_add_u32 s40, s40, s15
	s_addc_u32 s41, s41, 0
	s_mov_b32 s42, 0x10000
	s_mov_b32 s50, 0
	v_readlane_b32 s44, v252, 47
	v_readlane_b32 s45, v252, 48
	s_mul_i32 s15, s1, 0x58000
	s_lshl_b32 s19, s0, 7
	s_add_u32 s15, s15, s19
	s_add_u32 s44, s44, s15
	s_addc_u32 s45, s45, 0
	s_add_u32 s46, s44, 0x2c000
	s_addc_u32 s47, s45, 0
	v_mov_b32_e32 v50, v40
	v_mov_b32_e32 v51, v44
	s_branch .Lp0_issue
.Lp0_tA:
	s_cmpk_ge_u32 s13, 0xa40
	s_cbranch_scc1 .Lp0_twout
	s_sub_u32 s1, s13, 0x840
	s_and_b32 s0, s13, 15
	s_lshr_b32 s1, s1, 4
	s_lshl_b32 s15, s1, 8
	s_lshl_b32 s19, s0, 19
	s_add_u32 s15, s15, s19
	s_add_u32 s40, s68, s15
	s_addc_u32 s41, s69, 0
	s_mov_b32 s42, 0x20000
	v_readlane_b32 s48, v252, 24
	v_readlane_b32 s49, v252, 25
	s_lshl_b32 s15, s0, 8
	s_add_u32 s48, s48, s15
	s_addc_u32 s49, s49, 0
	s_mov_b32 s50, 1
	v_readlane_b32 s52, v253, 2
	v_readlane_b32 s53, v253, 3
	s_and_b64 s[52:53], s[52:53], exec
	s_cselect_b32 s51, 1, 0
	v_readlane_b32 s44, v252, 41
	v_readlane_b32 s45, v252, 42
	s_lshl_b32 s15, s1, 17
	s_lshl_b32 s19, s0, 7
	s_add_u32 s15, s15, s19
	s_add_u32 s44, s44, s15
	s_addc_u32 s45, s45, 0
	s_add_u32 s46, s44, 0x10000
	s_addc_u32 s47, s45, 0
	v_mov_b32_e32 v50, v41
	v_mov_b32_e32 v51, v43
	s_branch .Lp0_issue
.Lp0_twout:
	s_sub_u32 s1, s13, 0xa40
	s_and_b32 s0, s13, 15
	s_lshr_b32 s18, s1, 8
	s_bfe_u32 s1, s1, 0x40004
	s_lshl_b32 s15, s18, 22
	s_lshl_b32 s19, s1, 8
	s_add_u32 s15, s15, s19
	s_lshl_b32 s19, s0, 18
	s_add_u32 s15, s15, s19
	s_add_u32 s40, s64, s15
	s_addc_u32 s41, s65, 0
	s_mov_b32 s42, 0x10000
	s_mov_b32 s50, 0
	v_readlane_b32 s44, v252, 33
	v_readlane_b32 s45, v252, 34
	s_lshl_b32 s15, s18, 21
	s_lshl_b32 s19, s1, 17
	s_add_u32 s15, s15, s19
	s_lshl_b32 s19, s0, 7
	s_add_u32 s15, s15, s19
	s_add_u32 s44, s44, s15
	s_addc_u32 s45, s45, 0
	s_add_u32 s46, s44, 0x10000
	s_addc_u32 s47, s45, 0
	v_mov_b32_e32 v50, v40
	v_mov_b32_e32 v51, v43
.Lp0_issue:
	global_load_dwordx4 v[52:55], v50, s[40:41]
	s_add_u32 s40, s40, s42
	s_addc_u32 s41, s41, 0
	global_load_dwordx4 v[56:59], v50, s[40:41]
	s_add_u32 s40, s40, s42
	s_addc_u32 s41, s41, 0
	global_load_dwordx4 v[60:63], v50, s[40:41]
	s_add_u32 s40, s40, s42
	s_addc_u32 s41, s41, 0
	global_load_dwordx4 v[64:67], v50, s[40:41]
	s_cmp_eq_u32 s50, 0
	s_cbranch_scc1 .Lp0_s2
	v_mov_b32_e32 v68, 1.0
	v_mov_b32_e32 v70, 1.0
	v_mov_b32_e32 v72, 1.0
	v_mov_b32_e32 v74, 1.0
	s_cmp_eq_u32 s51, 0
	s_cbranch_scc1 .Lp0_s2
	global_load_dword v68, v45, s[48:49]
	global_load_dword v70, v45, s[48:49] offset:64
	global_load_dword v72, v45, s[48:49] offset:128
	global_load_dword v74, v45, s[48:49] offset:192
.Lp0_s2:
	s_cmp_eq_u32 s12, 0
	s_cbranch_scc1 .Lp0_rot
	s_waitcnt lgkmcnt(0)
	s_barrier
	ds_read2_b32 v[4:5], v34 offset1:32
	ds_read2_b32 v[6:7], v34 offset0:65 offset1:97
	ds_read2_b32 v[22:23], v34 offset0:130 offset1:162
	ds_read2_b32 v[24:25], v34 offset0:195 offset1:227
	ds_read2_b32 v[26:27], v35 offset0:4 offset1:36
	ds_read2_b32 v[36:37], v35 offset0:69 offset1:101
	ds_read2_b32 v[38:39], v35 offset0:134 offset1:166
	ds_read2_b32 v[10:11], v35 offset0:199 offset1:231
	s_waitcnt lgkmcnt(6)
	v_cvt_pk_bf16_f32 v0, v4, v6
	v_cvt_pk_bf16_f32 v12, v5, v7
	s_waitcnt lgkmcnt(4)
	v_cvt_pk_bf16_f32 v1, v22, v24
	v_cvt_pk_bf16_f32 v13, v23, v25
	s_waitcnt lgkmcnt(2)
	v_cvt_pk_bf16_f32 v2, v26, v36
	v_cvt_pk_bf16_f32 v14, v27, v37
	s_waitcnt lgkmcnt(0)
	v_cvt_pk_bf16_f32 v3, v38, v10
	v_cvt_pk_bf16_f32 v15, v39, v11
	global_store_dwordx4 v46, v[0:3], s[36:37]
	global_store_dwordx4 v46, v[12:15], s[38:39]
	s_barrier
.Lp0_rot:
	s_cmpk_ge_u32 s13, 0xc40
	s_cbranch_scc1 .Lp0_done
	s_mov_b64 s[36:37], s[44:45]
	s_mov_b64 s[38:39], s[46:47]
	v_mov_b32_e32 v46, v51
	s_mov_b32 s14, s50
	s_add_i32 s12, s12, 1
	s_min_u32 s12, s12, 2
	s_add_i32 s13, s13, s23
	s_branch .Lp0_loop
.Lp0_done:
	s_nop 1
